# baseline (speedup 1.0000x reference)
; __device__ __forceinline__ int opaque_tid() { int t; asm volatile("v_mov_b32 %0, %1" : "=v"(t) : "v"(threadIdx.x)); return t; }
; __device__ __forceinline__ void prep_weight(const float* src0, const float* src1, bf16_t* dst, int Nd, int K, int ld, int mode, float* tile, const float* wn = nullptr) {
;   const int tid = opaque_tid();
;   const int ntp = Nd >> 6, ntk = K >> 6, ntiles = ntp * ntk;
;   const int kl0 = tid >> 4, c4 = tid & 15;
;   auto tile_src = [&](int tix) -> const float* {
;     const int tp = tix % ntp, tk = tix / ntp;
;     const int p0 = tp * 64, k0 = tk * 64;
;     const float* src = src0; int col0 = p0;
;     if (mode == 1) { const int pn = p0 >> 8, rem = p0 & 255, bj = rem >> 7, j = rem & 127; src = bj ? src1 : src0; col0 = pn * 128 + j; }
;     else if (mode == 2) { const int t256 = p0 >> 8, rem = p0 & 255, bj = rem >> 7, w = rem & 127, head2 = w >> 6; col0 = t256 * 256 + head2 * 128 + bj * 64; }
;     return src + (size_t)(k0 + kl0) * ld + col0 + c4 * 4;
;   };
;   int tix = blockIdx.x;
;   f32x4 c0 = {0.f, 0.f, 0.f, 0.f}, c1 = c0;
;   if (tix < ntiles) { const float* sp = tile_src(tix); c0 = *(const f32x4*)sp; c1 = *(const f32x4*)(sp + (size_t)32 * ld); }
.LBB0_17:
	s_load_dwordx16 s[16:31], s[0:1], 0x0
	s_cmpk_lt_i32 s65, 0x1400
	s_cselect_b64 s[4:5], -1, 0
	v_writelane_b32 v252, s4, 4
	s_cmpk_gt_i32 s65, 0x13ff
	v_mov_b32 v8, v231
	s_nop 0
	v_writelane_b32 v252, s5, 5
	s_cbranch_scc1 .LBB0_24
	s_mul_hi_i32 s3, s65, 0x66666667
	s_lshr_b32 s4, s3, 31
	s_ashr_i32 s3, s3, 6
	s_add_i32 s3, s3, s4
	v_ashrrev_i32_e32 v20, 4, v8
	s_mul_i32 s4, s3, 0xa0
	s_sub_i32 s4, s65, s4
	v_lshl_add_u32 v2, s3, 6, v20
	s_mov_b32 s3, 0xa000
	s_waitcnt lgkmcnt(0)
	v_mov_b64_e32 v[0:1], s[26:27]
	s_lshl_b32 s4, s4, 6
	v_mad_i64_i32 v[0:1], s[6:7], v2, s3, v[0:1]
	v_lshlrev_b32_e32 v2, 2, v8
	s_ashr_i32 s5, s4, 31
	v_and_b32_e32 v10, 60, v2
	v_lshl_add_u64 v[0:1], s[4:5], 2, v[0:1]
	v_mov_b32_e32 v17, 0
	v_lshlrev_b32_e32 v16, 2, v10
	v_lshl_add_u64 v[12:13], v[0:1], 0, v[16:17]
	s_mov_b32 s4, 0x140000
	v_add_co_u32_e32 v14, vcc, s4, v12
	s_movk_i32 s4, 0x104
	s_nop 0
	v_addc_co_u32_e32 v15, vcc, 0, v13, vcc
	global_load_dwordx4 v[0:3], v[14:15], off nt
	global_load_dwordx4 v[4:7], v[12:13], off nt
	v_ashrrev_i32_e32 v22, 3, v8
	v_lshlrev_b32_e32 v8, 3, v8
	v_mul_lo_u32 v9, v20, s4
	v_and_b32_e32 v8, 56, v8
	v_add3_u32 v21, 0, v9, v16
	v_lshl_add_u32 v9, v22, 2, 0
	v_mul_u32_u24_e32 v11, 0x104, v8
	v_add_u32_e32 v25, v9, v11
	s_lshl_b32 s9, s65, 6
	s_lshl_b32 s8, s90, 6
	v_lshlrev_b32_e32 v16, 2, v10
	v_add_u32_e32 v23, 0x2080, v21
	v_add_u32_e32 v24, 0x2088, v21
	v_lshlrev_b32_e32 v18, 1, v8
	v_mov_b32_e32 v19, v17
	v_add_u32_e32 v26, 0x400, v25
	s_mov_b32 s12, s65
	s_branch .LBB0_20

; __device__ __forceinline__ int opaque_tid() { int t; asm volatile("v_mov_b32 %0, %1" : "=v"(t) : "v"(threadIdx.x)); return t; }
; __device__ __forceinline__ void prep_weight(const float* src0, const float* src1, bf16_t* dst, int Nd, int K, int ld, int mode, float* tile, const float* wn = nullptr) {
;   const int tid = opaque_tid();
;   const int ntp = Nd >> 6, ntk = K >> 6, ntiles = ntp * ntk;
;   const int kl0 = tid >> 4, c4 = tid & 15;
;   auto tile_src = [&](int tix) -> const float* {
;     const int tp = tix % ntp, tk = tix / ntp;
;     const int p0 = tp * 64, k0 = tk * 64;
;     const float* src = src0; int col0 = p0;
;     if (mode == 1) { const int pn = p0 >> 8, rem = p0 & 255, bj = rem >> 7, j = rem & 127; src = bj ? src1 : src0; col0 = pn * 128 + j; }
;     else if (mode == 2) { const int t256 = p0 >> 8, rem = p0 & 255, bj = rem >> 7, w = rem & 127, head2 = w >> 6; col0 = t256 * 256 + head2 * 128 + bj * 64; }
;     return src + (size_t)(k0 + kl0) * ld + col0 + c4 * 4;
;   };
;   int tix = blockIdx.x;
;   f32x4 c0 = {0.f, 0.f, 0.f, 0.f}, c1 = c0;
;   if (tix < ntiles) { const float* sp = tile_src(tix); c0 = *(const f32x4*)sp; c1 = *(const f32x4*)(sp + (size_t)32 * ld); }
;   for (; tix < ntiles; tix += gridDim.x) {
;     const int nx = tix + gridDim.x;
;     f32x4 n0 = c0, n1 = c1;
;     if (nx < ntiles) { const float* sp = tile_src(nx); n0 = *(const f32x4*)sp; n1 = *(const f32x4*)(sp + (size_t)32 * ld); }
.LBB0_22:
	s_waitcnt vmcnt(1)
	v_mov_b64_e32 v[14:15], v[2:3]
	s_waitcnt vmcnt(0)
	v_mov_b64_e32 v[10:11], v[6:7]
	s_andn2_b64 vcc, exec, s[6:7]
	v_mov_b64_e32 v[12:13], v[0:1]
	v_mov_b64_e32 v[8:9], v[4:5]
	s_cbranch_vccnz .LBB0_19
	s_mul_hi_i32 s6, s10, 0x66666667
	s_lshr_b32 s7, s6, 31
	s_ashr_i32 s6, s6, 6
	s_add_i32 s7, s6, s7
	s_mul_i32 s6, s7, 0xffffd800
	s_add_i32 s11, s8, s9
	s_add_i32 s6, s11, s6
	v_lshl_add_u32 v10, s7, 6, v20
	v_mov_b64_e32 v[8:9], s[26:27]
	v_mad_i64_i32 v[8:9], s[14:15], v10, s3, v[8:9]
	s_ashr_i32 s7, s6, 31
	v_lshl_add_u64 v[8:9], s[6:7], 2, v[8:9]
	v_lshl_add_u64 v[28:29], v[8:9], 0, v[16:17]
	v_add_co_u32_e32 v30, vcc, 0x140000, v28
	s_nop 1
	v_addc_co_u32_e32 v31, vcc, 0, v29, vcc
	global_load_dwordx4 v[8:11], v[28:29], off nt
	global_load_dwordx4 v[12:15], v[30:31], off nt
	s_branch .LBB0_19
.LBB0_24:
	s_waitcnt lgkmcnt(0)
	v_writelane_b32 v252, s16, 6
	v_mov_b32 v8, v231
	s_nop 1
	v_writelane_b32 v252, s17, 7
	v_writelane_b32 v252, s18, 8
	v_writelane_b32 v252, s19, 9
	v_writelane_b32 v252, s20, 10
	v_writelane_b32 v252, s21, 11
	v_writelane_b32 v252, s22, 12
	v_writelane_b32 v252, s23, 13
	v_writelane_b32 v252, s24, 14
	v_writelane_b32 v252, s25, 15
	v_writelane_b32 v252, s26, 16
	v_writelane_b32 v252, s27, 17
	v_writelane_b32 v252, s28, 18
	v_writelane_b32 v252, s29, 19
	v_writelane_b32 v252, s30, 20
	v_writelane_b32 v252, s31, 21
	s_load_dwordx16 s[4:19], s[0:1], 0x40
	s_add_u32 s0, s88, 0x2800000
	s_addc_u32 s1, s89, 0
	s_cmpk_lt_i32 s65, 0x400
	s_waitcnt lgkmcnt(0)
	v_writelane_b32 v252, s4, 22
	s_nop 1
	v_writelane_b32 v252, s5, 23
	v_writelane_b32 v252, s6, 24
	v_writelane_b32 v252, s7, 25
	v_writelane_b32 v252, s8, 26
	v_writelane_b32 v252, s9, 27
	v_writelane_b32 v252, s10, 28
	v_writelane_b32 v252, s11, 29
	v_writelane_b32 v252, s12, 30
	v_writelane_b32 v252, s13, 31
	v_writelane_b32 v252, s14, 32
	v_writelane_b32 v252, s15, 33
	v_writelane_b32 v252, s16, 34
	v_writelane_b32 v252, s17, 35
	v_writelane_b32 v252, s18, 36
	v_writelane_b32 v252, s19, 37
	v_writelane_b32 v252, s0, 38
	s_cselect_b64 s[4:5], -1, 0
	s_cmpk_gt_i32 s65, 0x3ff
	v_writelane_b32 v252, s1, 39
	s_cbranch_scc1 .LBB0_31
	s_ashr_i32 s0, s65, 31
	s_lshr_b32 s0, s0, 27
	s_add_i32 s1, s65, s0
	s_and_b32 s0, s1, 0x3ffffe0
	s_lshl_b32 s1, s1, 1
	v_ashrrev_i32_e32 v20, 4, v8
	s_andn2_b32 s1, s1, 63
	v_add_u32_e32 v0, s1, v20
	s_sub_i32 s0, s65, s0
	v_ashrrev_i32_e32 v1, 31, v0
	v_readlane_b32 s8, v252, 22
	s_lshl_b32 s0, s0, 6
	v_lshlrev_b64 v[0:1], 13, v[0:1]
	v_readlane_b32 s9, v252, 23
	v_lshlrev_b32_e32 v2, 2, v8
	s_ashr_i32 s1, s0, 31
	v_lshl_add_u64 v[0:1], s[8:9], 0, v[0:1]
	v_and_b32_e32 v10, 60, v2
	v_lshl_add_u64 v[0:1], s[0:1], 2, v[0:1]
	v_mov_b32_e32 v17, 0
	v_lshlrev_b32_e32 v16, 2, v10
	v_lshl_add_u64 v[4:5], v[0:1], 0, v[16:17]
	s_mov_b32 s0, 0x40000
	v_add_co_u32_e32 v0, vcc, s0, v4
	s_movk_i32 s0, 0x104
	s_nop 0
	v_addc_co_u32_e32 v1, vcc, 0, v5, vcc
	global_load_dwordx4 v[0:3], v[0:1], off nt
	s_nop 0
	global_load_dwordx4 v[4:7], v[4:5], off nt
	v_ashrrev_i32_e32 v22, 3, v8
	v_lshlrev_b32_e32 v8, 3, v8
	v_mul_lo_u32 v9, v20, s0
	v_and_b32_e32 v8, 56, v8
	v_add3_u32 v21, 0, v9, v16
	v_lshl_add_u32 v9, v22, 2, 0
	v_mul_u32_u24_e32 v11, 0x104, v8
	v_readlane_b32 s11, v252, 25
	v_add_u32_e32 v25, v9, v11
	s_lshl_b32 s8, s65, 6
	s_lshl_b32 s3, s90, 6
	v_lshlrev_b32_e32 v16, 2, v10
	v_add_u32_e32 v23, 0x2080, v21
	v_add_u32_e32 v24, 0x2088, v21
	v_lshlrev_b32_e32 v18, 1, v8
	v_mov_b32_e32 v19, v17
	v_add_u32_e32 v26, 0x400, v25
	s_mov_b32 s11, s65
	v_readlane_b32 s10, v252, 24
	v_readlane_b32 s12, v252, 26
	v_readlane_b32 s13, v252, 27
	v_readlane_b32 s14, v252, 28
	v_readlane_b32 s15, v252, 29
	v_readlane_b32 s16, v252, 30
	v_readlane_b32 s17, v252, 31
	v_readlane_b32 s18, v252, 32
	v_readlane_b32 s19, v252, 33
	v_readlane_b32 s20, v252, 34
	v_readlane_b32 s21, v252, 35
	v_readlane_b32 s22, v252, 36
	v_readlane_b32 s23, v252, 37
	s_branch .LBB0_27

; __device__ __forceinline__ int opaque_tid() { int t; asm volatile("v_mov_b32 %0, %1" : "=v"(t) : "v"(threadIdx.x)); return t; }
; __device__ __forceinline__ void prep_weight(const float* src0, const float* src1, bf16_t* dst, int Nd, int K, int ld, int mode, float* tile, const float* wn = nullptr) {
;   const int tid = opaque_tid();
;   const int ntp = Nd >> 6, ntk = K >> 6, ntiles = ntp * ntk;
;   const int kl0 = tid >> 4, c4 = tid & 15;
;   auto tile_src = [&](int tix) -> const float* {
;     const int tp = tix % ntp, tk = tix / ntp;
;     const int p0 = tp * 64, k0 = tk * 64;
;     const float* src = src0; int col0 = p0;
;     if (mode == 1) { const int pn = p0 >> 8, rem = p0 & 255, bj = rem >> 7, j = rem & 127; src = bj ? src1 : src0; col0 = pn * 128 + j; }
;     else if (mode == 2) { const int t256 = p0 >> 8, rem = p0 & 255, bj = rem >> 7, w = rem & 127, head2 = w >> 6; col0 = t256 * 256 + head2 * 128 + bj * 64; }
;     return src + (size_t)(k0 + kl0) * ld + col0 + c4 * 4;
;   };
;   int tix = blockIdx.x;
;   f32x4 c0 = {0.f, 0.f, 0.f, 0.f}, c1 = c0;
;   if (tix < ntiles) { const float* sp = tile_src(tix); c0 = *(const f32x4*)sp; c1 = *(const f32x4*)(sp + (size_t)32 * ld); }
;   for (; tix < ntiles; tix += gridDim.x) {
;     const int nx = tix + gridDim.x;
;     f32x4 n0 = c0, n1 = c1;
;     if (nx < ntiles) { const float* sp = tile_src(nx); n0 = *(const f32x4*)sp; n1 = *(const f32x4*)(sp + (size_t)32 * ld); }
.LBB0_29:
	s_waitcnt vmcnt(1)
	v_mov_b64_e32 v[14:15], v[2:3]
	s_waitcnt vmcnt(0)
	v_mov_b64_e32 v[10:11], v[6:7]
	s_andn2_b64 vcc, exec, s[6:7]
	v_mov_b64_e32 v[12:13], v[0:1]
	v_mov_b64_e32 v[8:9], v[4:5]
	s_cbranch_vccnz .LBB0_26
	s_ashr_i32 s6, s9, 31
	s_lshr_b32 s6, s6, 27
	s_add_i32 s6, s9, s6
	s_ashr_i32 s7, s6, 5
	v_lshl_add_u32 v8, s7, 6, v20
	s_add_i32 s10, s3, s8
	s_lshl_b32 s6, s7, 11
	v_ashrrev_i32_e32 v9, 31, v8
	v_readlane_b32 s12, v252, 22
	s_sub_i32 s6, s10, s6
	v_lshlrev_b64 v[8:9], 13, v[8:9]
	v_readlane_b32 s13, v252, 23
	s_ashr_i32 s7, s6, 31
	v_readlane_b32 s14, v252, 24
	v_lshl_add_u64 v[8:9], s[12:13], 0, v[8:9]
	v_lshl_add_u64 v[8:9], s[6:7], 2, v[8:9]
	v_lshl_add_u64 v[8:9], v[8:9], 0, v[16:17]
	v_add_co_u32_e32 v12, vcc, 0x40000, v8
	v_readlane_b32 s15, v252, 25
	s_nop 0
	v_addc_co_u32_e32 v13, vcc, 0, v9, vcc
	global_load_dwordx4 v[8:11], v[8:9], off nt
	s_nop 0
	global_load_dwordx4 v[12:15], v[12:13], off nt
	v_readlane_b32 s16, v252, 26
	v_readlane_b32 s17, v252, 27
	v_readlane_b32 s18, v252, 28
	v_readlane_b32 s19, v252, 29
	v_readlane_b32 s20, v252, 30
	v_readlane_b32 s21, v252, 31
	v_readlane_b32 s22, v252, 32
	v_readlane_b32 s23, v252, 33
	v_readlane_b32 s24, v252, 34
	v_readlane_b32 s25, v252, 35
	v_readlane_b32 s26, v252, 36
	v_readlane_b32 s27, v252, 37
	s_branch .LBB0_26
.LBB0_31:
	s_cmpk_lt_i32 s65, 0x1600
	s_cselect_b64 s[6:7], -1, 0
	s_cmpk_gt_i32 s65, 0x15ff
	s_mul_hi_i32 s3, s65, 0x2e8ba2e9
	v_mov_b32 v8, v231
	s_cbranch_scc1 .LBB0_40
	s_add_u32 s8, s88, 0x3000000
	s_addc_u32 s9, s89, 0
	s_lshr_b32 s0, s3, 31
	s_ashr_i32 s1, s3, 5
	s_add_i32 s1, s1, s0
	s_mul_i32 s0, s1, 0xb0
	s_sub_i32 s0, s65, s0
	s_lshl_b32 s10, s0, 6
	s_and_b32 s10, s10, 64
	s_bitcmp0_b32 s0, 1
	v_ashrrev_i32_e32 v23, 4, v8
	s_cselect_b32 s11, s45, s47
	s_cselect_b32 s12, s44, s46
	s_lshl_b32 s0, s0, 5
	v_mov_b32_e32 v0, s12
	v_mov_b32_e32 v1, s11
	s_and_b32 s0, s0, 0xffffff80
	v_lshl_add_u32 v2, s1, 6, v23
	s_movk_i32 s14, 0x5800
	s_or_b32 s0, s0, s10
	v_mad_i64_i32 v[0:1], s[10:11], v2, s14, v[0:1]
	v_lshlrev_b32_e32 v2, 2, v8
	s_ashr_i32 s1, s0, 31
	v_and_b32_e32 v10, 60, v2
	v_lshl_add_u64 v[0:1], s[0:1], 2, v[0:1]
	v_mov_b32_e32 v17, 0
	v_lshlrev_b32_e32 v16, 2, v10
	v_lshl_add_u64 v[4:5], v[0:1], 0, v[16:17]
	s_mov_b32 s0, 0xb0000
	v_add_co_u32_e32 v0, vcc, s0, v4
	v_readlane_b32 s16, v252, 6
	s_nop 0
	v_addc_co_u32_e32 v1, vcc, 0, v5, vcc
	global_load_dwordx4 v[0:3], v[0:1], off nt
	s_nop 0
	global_load_dwordx4 v[4:7], v[4:5], off nt
	v_readlane_b32 s22, v252, 12
	v_readlane_b32 s23, v252, 13
	s_movk_i32 s0, 0x104
	v_ashrrev_i32_e32 v25, 3, v8
	v_lshlrev_b32_e32 v8, 3, v8
	s_cmp_lg_u64 s[22:23], 0
	v_mul_lo_u32 v9, v23, s0
	v_and_b32_e32 v8, 56, v8
	s_cselect_b64 s[0:1], -1, 0
	v_lshl_add_u32 v11, v25, 2, 0
	v_mul_u32_u24_e32 v12, 0x104, v8
	v_lshlrev_b32_e32 v18, 1, v8
	v_cndmask_b32_e64 v8, 0, 1, s[0:1]
	v_add3_u32 v26, 0, v9, v16
	v_add_u32_e32 v27, v11, v12
	v_readlane_b32 s17, v252, 7
	v_readlane_b32 s18, v252, 8
	s_add_i32 s10, s90, s65
	v_lshlrev_b32_e32 v16, 2, v10
	v_cmp_ne_u32_e64 s[0:1], 1, v8
	s_mov_b32 s12, s65
	v_mov_b32_e32 v19, v17
	v_add_u32_e32 v28, 0x2080, v26
	v_add_u32_e32 v29, 0x2088, v26
	v_add_u32_e32 v30, 0x400, v27
	s_lshl_b32 s15, s65, 6
	s_lshl_b32 s16, s90, 6
	s_lshl_b32 s17, s90, 5
	s_lshl_b32 s18, s10, 5
	v_readlane_b32 s19, v252, 9
	v_readlane_b32 s20, v252, 10
	v_readlane_b32 s21, v252, 11
	v_readlane_b32 s24, v252, 14
	v_readlane_b32 s25, v252, 15
	v_readlane_b32 s26, v252, 16
	v_readlane_b32 s27, v252, 17
	v_readlane_b32 s28, v252, 18
	v_readlane_b32 s29, v252, 19
	v_readlane_b32 s30, v252, 20
	v_readlane_b32 s31, v252, 21
	s_waitcnt vmcnt(1)
	v_mov_b64_e32 v[14:15], v[2:3]
	s_waitcnt vmcnt(0)
	v_mov_b64_e32 v[10:11], v[6:7]
	v_mov_b64_e32 v[12:13], v[0:1]
	v_mov_b64_e32 v[8:9], v[4:5]
	s_branch .LBB0_34

; __device__ __forceinline__ void prep_weight(const float* src0, const float* src1, bf16_t* dst, int Nd, int K, int ld, int mode, float* tile, const float* wn = nullptr) {
;     ...
;   auto tile_src = [&](int tix) -> const float* {
;     const int tp = tix % ntp, tk = tix / ntp;
;     const int p0 = tp * 64, k0 = tk * 64;
;     const float* src = src0; int col0 = p0;
;     if (mode == 1) { const int pn = p0 >> 8, rem = p0 & 255, bj = rem >> 7, j = rem & 127; src = bj ? src1 : src0; col0 = pn * 128 + j; }
;     else if (mode == 2) { const int t256 = p0 >> 8, rem = p0 & 255, bj = rem >> 7, w = rem & 127, head2 = w >> 6; col0 = t256 * 256 + head2 * 128 + bj * 64; }
;     return src + (size_t)(k0 + kl0) * ld + col0 + c4 * 4;
;   };
;   int tix = blockIdx.x;
;   f32x4 c0 = {0.f, 0.f, 0.f, 0.f}, c1 = c0;
;   if (tix < ntiles) { const float* sp = tile_src(tix); c0 = *(const f32x4*)sp; c1 = *(const f32x4*)(sp + (size_t)32 * ld); }
;   for (; tix < ntiles; tix += gridDim.x) {
;     const int nx = tix + gridDim.x;
;     f32x4 n0 = c0, n1 = c1;
;     if (nx < ntiles) { const float* sp = tile_src(nx); n0 = *(const f32x4*)sp; n1 = *(const f32x4*)(sp + (size_t)32 * ld); }
.LBB0_34:
	s_add_i32 s19, s12, s90
	s_cmpk_gt_i32 s19, 0x15ff
	s_cselect_b64 s[10:11], -1, 0
	s_and_b64 vcc, exec, s[10:11]
	s_cbranch_vccnz .LBB0_36
	s_mul_hi_i32 s13, s19, 0x2e8ba2e9
	s_lshr_b32 s20, s13, 31
	s_ashr_i32 s13, s13, 5
	s_add_i32 s13, s13, s20
	s_add_i32 s20, s16, s15
	s_and_b32 s20, s20, 64
	s_bitcmp0_b32 s19, 1
	s_cselect_b32 s21, s45, s47
	v_mov_b32_e32 v9, s21
	s_mul_i32 s21, s13, 0xffffea00
	s_cselect_b32 s22, s44, s46
	s_add_i32 s21, s18, s21
	s_and_b32 s21, s21, 0xffffff80
	v_mov_b32_e32 v8, s22
	s_or_b32 s20, s21, s20
	v_lshl_add_u32 v10, s13, 6, v23
	v_mad_i64_i32 v[8:9], s[22:23], v10, s14, v[8:9]
	s_ashr_i32 s21, s20, 31
	v_lshl_add_u64 v[8:9], s[20:21], 2, v[8:9]
	v_lshl_add_u64 v[8:9], v[8:9], 0, v[16:17]
	v_add_co_u32_e32 v12, vcc, 0xb0000, v8
	s_nop 1
	v_addc_co_u32_e32 v13, vcc, 0, v9, vcc
	global_load_dwordx4 v[8:11], v[8:9], off nt
	s_nop 0
	global_load_dwordx4 v[12:15], v[12:13], off nt

; __device__ __forceinline__ int opaque_tid() { int t; asm volatile("v_mov_b32 %0, %1" : "=v"(t) : "v"(threadIdx.x)); return t; }
; __device__ __forceinline__ void prep_weight(const float* src0, const float* src1, bf16_t* dst, int Nd, int K, int ld, int mode, float* tile, const float* wn = nullptr) {
;   const int tid = opaque_tid();
;   const int ntp = Nd >> 6, ntk = K >> 6, ntiles = ntp * ntk;
;   const int kl0 = tid >> 4, c4 = tid & 15;
;   auto tile_src = [&](int tix) -> const float* {
;     const int tp = tix % ntp, tk = tix / ntp;
;     const int p0 = tp * 64, k0 = tk * 64;
;     const float* src = src0; int col0 = p0;
;     if (mode == 1) { const int pn = p0 >> 8, rem = p0 & 255, bj = rem >> 7, j = rem & 127; src = bj ? src1 : src0; col0 = pn * 128 + j; }
;     else if (mode == 2) { const int t256 = p0 >> 8, rem = p0 & 255, bj = rem >> 7, w = rem & 127, head2 = w >> 6; col0 = t256 * 256 + head2 * 128 + bj * 64; }
;     return src + (size_t)(k0 + kl0) * ld + col0 + c4 * 4;
;   };
;   int tix = blockIdx.x;
;   f32x4 c0 = {0.f, 0.f, 0.f, 0.f}, c1 = c0;
;   if (tix < ntiles) { const float* sp = tile_src(tix); c0 = *(const f32x4*)sp; c1 = *(const f32x4*)(sp + (size_t)32 * ld); }
.LBB0_40:
	s_cmpk_lt_i32 s65, 0xb00
	s_cselect_b64 s[0:1], -1, 0
	s_cmpk_gt_i32 s65, 0xaff
	v_mov_b32 v8, v231
	s_cbranch_scc1 .LBB0_47
	s_add_u32 s8, s88, 0x5c00000
	s_addc_u32 s9, s89, 0
	s_ashr_i32 s10, s65, 31
	s_lshr_b32 s10, s10, 27
	s_add_i32 s11, s65, s10
	s_and_b32 s10, s11, 0x3ffffe0
	s_lshl_b32 s11, s11, 1
	v_ashrrev_i32_e32 v22, 4, v8
	s_andn2_b32 s11, s11, 63
	v_add_u32_e32 v0, s11, v22
	s_sub_i32 s10, s65, s10
	v_ashrrev_i32_e32 v1, 31, v0
	s_lshl_b32 s10, s10, 6
	v_lshlrev_b64 v[0:1], 13, v[0:1]
	v_lshlrev_b32_e32 v2, 2, v8
	v_lshl_add_u64 v[0:1], s[48:49], 0, v[0:1]
	s_ashr_i32 s11, s10, 31
	v_and_b32_e32 v10, 60, v2
	v_lshl_add_u64 v[0:1], s[10:11], 2, v[0:1]
	v_mov_b32_e32 v17, 0
	v_lshlrev_b32_e32 v16, 2, v10
	v_lshl_add_u64 v[4:5], v[0:1], 0, v[16:17]
	s_mov_b32 s10, 0x40000
	v_add_co_u32_e32 v0, vcc, s10, v4
	s_movk_i32 s10, 0x104
	s_nop 0
	v_addc_co_u32_e32 v1, vcc, 0, v5, vcc
	global_load_dwordx4 v[0:3], v[0:1], off nt
	s_nop 0
	global_load_dwordx4 v[4:7], v[4:5], off nt
	v_ashrrev_i32_e32 v24, 3, v8
	v_lshlrev_b32_e32 v8, 3, v8
	v_mul_lo_u32 v9, v22, s10
	v_and_b32_e32 v8, 56, v8
	v_add3_u32 v23, 0, v9, v16
	v_lshl_add_u32 v9, v24, 2, 0
	v_mul_u32_u24_e32 v11, 0x104, v8
	v_add_u32_e32 v27, v9, v11
	s_lshl_b32 s14, s65, 6
	s_lshl_b32 s12, s90, 6
	v_lshlrev_b32_e32 v16, 2, v10
	v_add_u32_e32 v25, 0x2080, v23
	v_add_u32_e32 v26, 0x2088, v23
	s_movk_i32 s13, 0x2c00
	v_mov_b64_e32 v[18:19], s[8:9]
	v_lshlrev_b32_e32 v20, 1, v8
	v_mov_b32_e32 v21, v17
	v_add_u32_e32 v28, 0x400, v27
	s_mov_b32 s17, s65
	s_branch .LBB0_43

; __device__ __forceinline__ int opaque_tid() { int t; asm volatile("v_mov_b32 %0, %1" : "=v"(t) : "v"(threadIdx.x)); return t; }
; __device__ __forceinline__ void prep_weight(const float* src0, const float* src1, bf16_t* dst, int Nd, int K, int ld, int mode, float* tile, const float* wn = nullptr) {
;   const int tid = opaque_tid();
;   const int ntp = Nd >> 6, ntk = K >> 6, ntiles = ntp * ntk;
;   const int kl0 = tid >> 4, c4 = tid & 15;
;   auto tile_src = [&](int tix) -> const float* {
;     const int tp = tix % ntp, tk = tix / ntp;
;     const int p0 = tp * 64, k0 = tk * 64;
;     const float* src = src0; int col0 = p0;
;     if (mode == 1) { const int pn = p0 >> 8, rem = p0 & 255, bj = rem >> 7, j = rem & 127; src = bj ? src1 : src0; col0 = pn * 128 + j; }
;     else if (mode == 2) { const int t256 = p0 >> 8, rem = p0 & 255, bj = rem >> 7, w = rem & 127, head2 = w >> 6; col0 = t256 * 256 + head2 * 128 + bj * 64; }
;     return src + (size_t)(k0 + kl0) * ld + col0 + c4 * 4;
;   };
;   int tix = blockIdx.x;
;   f32x4 c0 = {0.f, 0.f, 0.f, 0.f}, c1 = c0;
;   if (tix < ntiles) { const float* sp = tile_src(tix); c0 = *(const f32x4*)sp; c1 = *(const f32x4*)(sp + (size_t)32 * ld); }
;   for (; tix < ntiles; tix += gridDim.x) {
;     const int nx = tix + gridDim.x;
;     f32x4 n0 = c0, n1 = c1;
;     if (nx < ntiles) { const float* sp = tile_src(nx); n0 = *(const f32x4*)sp; n1 = *(const f32x4*)(sp + (size_t)32 * ld); }
.LBB0_45:
	s_waitcnt vmcnt(1)
	v_mov_b64_e32 v[14:15], v[2:3]
	s_waitcnt vmcnt(0)
	v_mov_b64_e32 v[10:11], v[6:7]
	s_andn2_b64 vcc, exec, s[10:11]
	v_mov_b64_e32 v[12:13], v[0:1]
	v_mov_b64_e32 v[8:9], v[4:5]
	s_cbranch_vccnz .LBB0_42
	s_ashr_i32 s10, s15, 31
	s_lshr_b32 s10, s10, 27
	s_add_i32 s10, s15, s10
	s_ashr_i32 s11, s10, 5
	v_lshl_add_u32 v8, s11, 6, v22
	s_add_i32 s16, s12, s14
	s_lshl_b32 s10, s11, 11
	v_ashrrev_i32_e32 v9, 31, v8
	s_sub_i32 s10, s16, s10
	v_lshlrev_b64 v[8:9], 13, v[8:9]
	v_lshl_add_u64 v[8:9], s[48:49], 0, v[8:9]
	s_ashr_i32 s11, s10, 31
	v_lshl_add_u64 v[8:9], s[10:11], 2, v[8:9]
	v_lshl_add_u64 v[8:9], v[8:9], 0, v[16:17]
	v_add_co_u32_e32 v12, vcc, 0x40000, v8
	s_nop 1
	v_addc_co_u32_e32 v13, vcc, 0, v9, vcc
	global_load_dwordx4 v[8:11], v[8:9], off nt
	s_nop 0
	global_load_dwordx4 v[12:15], v[12:13], off nt
	s_branch .LBB0_42
.LBB0_47:
	s_add_u32 s8, s88, 0x7200000
	s_addc_u32 s9, s89, 0
	v_writelane_b32 v252, s8, 40
	s_cmpk_lt_i32 s65, 0xc00
	v_mov_b32 v8, v231
	s_nop 0
	v_writelane_b32 v252, s9, 41
	s_cselect_b64 s[8:9], -1, 0
	v_writelane_b32 v252, s8, 42
	s_cmpk_gt_i32 s65, 0xbff
	s_nop 0
	v_writelane_b32 v252, s9, 43
	s_cbranch_scc1 .LBB0_54
	v_readlane_b32 s8, v252, 6
	v_readlane_b32 s10, v252, 8
	v_readlane_b32 s12, v252, 10
	v_readlane_b32 s9, v252, 7
	v_readlane_b32 s11, v252, 9
	v_readlane_b32 s13, v252, 11
	s_add_u32 s8, s12, 0x2000
	s_mul_hi_i32 s10, s65, 0x2aaaaaab
	s_addc_u32 s9, s13, 0
	s_lshr_b32 s11, s10, 31
	s_ashr_i32 s10, s10, 4
	s_add_i32 s11, s10, s11
	s_mul_i32 s10, s11, 0x60
	v_readlane_b32 s16, v252, 14
	v_readlane_b32 s17, v252, 15
	v_readlane_b32 s18, v252, 16
	v_readlane_b32 s19, v252, 17
	v_readlane_b32 s20, v252, 18
	v_readlane_b32 s21, v252, 19
	v_readlane_b32 s22, v252, 20
	v_readlane_b32 s23, v252, 21
	s_sub_i32 s10, s65, s10
	s_lshl_b32 s12, s10, 6
	s_lshl_b32 s13, s10, 7
	v_readlane_b32 s16, v252, 22
	v_readlane_b32 s14, v252, 12
	v_ashrrev_i32_e32 v20, 4, v8
	s_and_b32 s12, s12, 0xffffff00
	s_and_b32 s13, s13, 0x80
	s_lshl_b32 s10, s10, 5
	v_readlane_b32 s18, v252, 24
	v_readlane_b32 s19, v252, 25
	s_or_b32 s12, s12, s13
	s_and_b32 s10, s10, 64
	v_lshl_add_u32 v2, s11, 6, v20
	s_movk_i32 s14, 0x6000
	v_mov_b64_e32 v[0:1], s[18:19]
	s_or_b32 s10, s12, s10
	v_mad_i64_i32 v[0:1], s[12:13], v2, s14, v[0:1]
	v_lshlrev_b32_e32 v2, 2, v8
	s_ashr_i32 s11, s10, 31
	v_and_b32_e32 v10, 60, v2
	v_lshl_add_u64 v[0:1], s[10:11], 2, v[0:1]
	v_mov_b32_e32 v17, 0
	v_lshlrev_b32_e32 v16, 2, v10
	v_lshl_add_u64 v[0:1], v[0:1], 0, v[16:17]
	s_mov_b32 s10, 0xc0000
	v_add_co_u32_e32 v2, vcc, s10, v0
	s_movk_i32 s10, 0x104
	s_nop 0
	v_addc_co_u32_e32 v3, vcc, 0, v1, vcc
	global_load_dwordx4 v[4:7], v[2:3], off nt
	s_nop 0
	global_load_dwordx4 v[0:3], v[0:1], off nt
	v_ashrrev_i32_e32 v22, 3, v8
	v_lshlrev_b32_e32 v8, 3, v8
	v_mul_lo_u32 v9, v20, s10
	v_and_b32_e32 v8, 56, v8
	v_add3_u32 v21, 0, v9, v16
	v_lshl_add_u32 v9, v22, 2, 0
	v_mul_u32_u24_e32 v11, 0x104, v8
	v_readlane_b32 s15, v252, 13
	v_readlane_b32 s17, v252, 23
	v_readlane_b32 s21, v252, 27
	s_add_i32 s10, s90, s65
	v_add_u32_e32 v25, v9, v11
	s_lshl_b32 s16, s65, 6
	s_lshl_b32 s15, s90, 6
	s_lshl_b32 s17, s10, 7
	s_lshl_b32 s18, s90, 7
	v_lshlrev_b32_e32 v16, 2, v10
	v_add_u32_e32 v23, 0x2080, v21
	v_add_u32_e32 v24, 0x2088, v21
	v_lshlrev_b32_e32 v18, 1, v8
	v_mov_b32_e32 v19, v17
	v_add_u32_e32 v26, 0x400, v25
	s_mov_b32 s21, s65
	v_readlane_b32 s20, v252, 26
	v_readlane_b32 s22, v252, 28
	v_readlane_b32 s23, v252, 29
	v_readlane_b32 s24, v252, 30
	v_readlane_b32 s25, v252, 31
	v_readlane_b32 s26, v252, 32
	v_readlane_b32 s27, v252, 33
	v_readlane_b32 s28, v252, 34
	v_readlane_b32 s29, v252, 35
	v_readlane_b32 s30, v252, 36
	v_readlane_b32 s31, v252, 37
	s_branch .LBB0_50

; __device__ __forceinline__ int opaque_tid() { int t; asm volatile("v_mov_b32 %0, %1" : "=v"(t) : "v"(threadIdx.x)); return t; }
; __device__ __forceinline__ void prep_weight(const float* src0, const float* src1, bf16_t* dst, int Nd, int K, int ld, int mode, float* tile, const float* wn = nullptr) {
;   const int tid = opaque_tid();
;   const int ntp = Nd >> 6, ntk = K >> 6, ntiles = ntp * ntk;
;   const int kl0 = tid >> 4, c4 = tid & 15;
;   auto tile_src = [&](int tix) -> const float* {
;     const int tp = tix % ntp, tk = tix / ntp;
;     const int p0 = tp * 64, k0 = tk * 64;
;     const float* src = src0; int col0 = p0;
;     if (mode == 1) { const int pn = p0 >> 8, rem = p0 & 255, bj = rem >> 7, j = rem & 127; src = bj ? src1 : src0; col0 = pn * 128 + j; }
;     else if (mode == 2) { const int t256 = p0 >> 8, rem = p0 & 255, bj = rem >> 7, w = rem & 127, head2 = w >> 6; col0 = t256 * 256 + head2 * 128 + bj * 64; }
;     return src + (size_t)(k0 + kl0) * ld + col0 + c4 * 4;
;   };
;   int tix = blockIdx.x;
;   f32x4 c0 = {0.f, 0.f, 0.f, 0.f}, c1 = c0;
;   if (tix < ntiles) { const float* sp = tile_src(tix); c0 = *(const f32x4*)sp; c1 = *(const f32x4*)(sp + (size_t)32 * ld); }
;   for (; tix < ntiles; tix += gridDim.x) {
;     const int nx = tix + gridDim.x;
;     f32x4 n0 = c0, n1 = c1;
;     if (nx < ntiles) { const float* sp = tile_src(nx); n0 = *(const f32x4*)sp; n1 = *(const f32x4*)(sp + (size_t)32 * ld); }
.LBB0_52:
	s_waitcnt vmcnt(1)
	v_mov_b64_e32 v[10:11], v[6:7]
	s_waitcnt vmcnt(0)
	v_mov_b64_e32 v[14:15], v[2:3]
	s_andn2_b64 vcc, exec, s[12:13]
	v_mov_b64_e32 v[8:9], v[4:5]
	v_mov_b64_e32 v[12:13], v[0:1]
	s_cbranch_vccnz .LBB0_49
	s_mul_hi_i32 s12, s19, 0x2aaaaaab
	s_lshr_b32 s13, s12, 31
	s_ashr_i32 s12, s12, 4
	s_add_i32 s13, s12, s13
	s_mul_i32 s12, s13, 0xffffe800
	s_add_i32 s20, s15, s16
	s_add_i32 s12, s20, s12
	s_and_b32 s22, s12, 0xffffff00
	s_and_b32 s23, s17, 0x80
	s_lshr_b32 s12, s12, 1
	v_readlane_b32 s68, v252, 22
	s_or_b32 s22, s22, s23
	s_and_b32 s12, s12, 64
	v_readlane_b32 s70, v252, 24
	v_readlane_b32 s71, v252, 25
	s_or_b32 s12, s22, s12
	v_lshl_add_u32 v10, s13, 6, v20
	v_mov_b64_e32 v[8:9], s[70:71]
	v_mad_i64_i32 v[8:9], s[22:23], v10, s14, v[8:9]
	s_ashr_i32 s13, s12, 31
	v_lshl_add_u64 v[8:9], s[12:13], 2, v[8:9]
	v_lshl_add_u64 v[8:9], v[8:9], 0, v[16:17]
	v_add_co_u32_e32 v10, vcc, 0xc0000, v8
	v_readlane_b32 s69, v252, 23
	s_nop 0
	v_addc_co_u32_e32 v11, vcc, 0, v9, vcc
	global_load_dwordx4 v[12:15], v[8:9], off nt
	s_nop 0
	global_load_dwordx4 v[8:11], v[10:11], off nt
	v_readlane_b32 s72, v252, 26
	v_readlane_b32 s73, v252, 27
	v_readlane_b32 s74, v252, 28
	v_readlane_b32 s75, v252, 29
	v_readlane_b32 s76, v252, 30
	v_readlane_b32 s77, v252, 31
	v_readlane_b32 s78, v252, 32
	v_readlane_b32 s79, v252, 33
	v_readlane_b32 s80, v252, 34
	v_readlane_b32 s81, v252, 35
	v_readlane_b32 s82, v252, 36
	v_readlane_b32 s83, v252, 37
	s_branch .LBB0_49
.LBB0_54:
	s_add_u32 s8, s88, 0x8a00000
	s_addc_u32 s9, s89, 0
	v_writelane_b32 v252, s8, 44
	v_cndmask_b32_e64 v0, 0, 1, s[4:5]
	s_andn2_b64 vcc, exec, s[4:5]
	v_writelane_b32 v252, s9, 45
	v_cmp_ne_u32_e64 s[8:9], 1, v0
	v_mov_b32 v8, v231
	s_nop 1
	v_writelane_b32 v252, s8, 46
	s_nop 1
	v_writelane_b32 v252, s9, 47
	s_cbranch_vccnz .LBB0_61
	s_ashr_i32 s4, s65, 31
	s_lshr_b32 s4, s4, 27
	s_add_i32 s5, s65, s4
	s_and_b32 s4, s5, 0x3ffffe0
	s_lshl_b32 s5, s5, 1
	v_ashrrev_i32_e32 v20, 4, v8
	s_andn2_b32 s5, s5, 63
	v_add_u32_e32 v0, s5, v20
	s_sub_i32 s4, s65, s4
	v_ashrrev_i32_e32 v1, 31, v0
	v_readlane_b32 s8, v252, 22
	s_lshl_b32 s4, s4, 6
	v_lshlrev_b64 v[0:1], 13, v[0:1]
	v_readlane_b32 s22, v252, 36
	v_readlane_b32 s23, v252, 37
	v_lshlrev_b32_e32 v2, 2, v8
	s_ashr_i32 s5, s4, 31
	v_lshl_add_u64 v[0:1], s[22:23], 0, v[0:1]
	v_and_b32_e32 v10, 60, v2
	v_lshl_add_u64 v[0:1], s[4:5], 2, v[0:1]
	v_mov_b32_e32 v17, 0
	v_lshlrev_b32_e32 v16, 2, v10
	v_lshl_add_u64 v[4:5], v[0:1], 0, v[16:17]
	s_mov_b32 s4, 0x40000
	v_add_co_u32_e32 v0, vcc, s4, v4
	s_movk_i32 s4, 0x104
	s_nop 0
	v_addc_co_u32_e32 v1, vcc, 0, v5, vcc
	global_load_dwordx4 v[0:3], v[0:1], off nt
	s_nop 0
	global_load_dwordx4 v[4:7], v[4:5], off nt
	v_ashrrev_i32_e32 v22, 3, v8
	v_lshlrev_b32_e32 v8, 3, v8
	v_mul_lo_u32 v9, v20, s4
	v_and_b32_e32 v8, 56, v8
	v_add3_u32 v21, 0, v9, v16
	v_lshl_add_u32 v9, v22, 2, 0
	v_mul_u32_u24_e32 v11, 0x104, v8
	v_readlane_b32 s10, v252, 24
	v_readlane_b32 s11, v252, 25
	v_readlane_b32 s14, v252, 28
	v_add_u32_e32 v25, v9, v11
	s_lshl_b32 s11, s65, 6
	s_lshl_b32 s10, s90, 6
	v_lshlrev_b32_e32 v16, 2, v10
	v_add_u32_e32 v23, 0x2080, v21
	v_add_u32_e32 v24, 0x2088, v21
	v_lshlrev_b32_e32 v18, 1, v8
	v_mov_b32_e32 v19, v17
	v_add_u32_e32 v26, 0x400, v25
	s_mov_b32 s14, s65
	v_readlane_b32 s9, v252, 23
	v_readlane_b32 s12, v252, 26
	v_readlane_b32 s13, v252, 27
	v_readlane_b32 s15, v252, 29
	v_readlane_b32 s16, v252, 30
	v_readlane_b32 s17, v252, 31
	v_readlane_b32 s18, v252, 32
	v_readlane_b32 s19, v252, 33
	v_readlane_b32 s20, v252, 34
	v_readlane_b32 s21, v252, 35
	s_branch .LBB0_57

; __device__ __forceinline__ int opaque_tid() { int t; asm volatile("v_mov_b32 %0, %1" : "=v"(t) : "v"(threadIdx.x)); return t; }
; __device__ __forceinline__ void prep_weight(const float* src0, const float* src1, bf16_t* dst, int Nd, int K, int ld, int mode, float* tile, const float* wn = nullptr) {
;   const int tid = opaque_tid();
;   const int ntp = Nd >> 6, ntk = K >> 6, ntiles = ntp * ntk;
;   const int kl0 = tid >> 4, c4 = tid & 15;
;   auto tile_src = [&](int tix) -> const float* {
;     const int tp = tix % ntp, tk = tix / ntp;
;     const int p0 = tp * 64, k0 = tk * 64;
;     const float* src = src0; int col0 = p0;
;     if (mode == 1) { const int pn = p0 >> 8, rem = p0 & 255, bj = rem >> 7, j = rem & 127; src = bj ? src1 : src0; col0 = pn * 128 + j; }
;     else if (mode == 2) { const int t256 = p0 >> 8, rem = p0 & 255, bj = rem >> 7, w = rem & 127, head2 = w >> 6; col0 = t256 * 256 + head2 * 128 + bj * 64; }
;     return src + (size_t)(k0 + kl0) * ld + col0 + c4 * 4;
;   };
;   int tix = blockIdx.x;
;   f32x4 c0 = {0.f, 0.f, 0.f, 0.f}, c1 = c0;
;   if (tix < ntiles) { const float* sp = tile_src(tix); c0 = *(const f32x4*)sp; c1 = *(const f32x4*)(sp + (size_t)32 * ld); }
;   for (; tix < ntiles; tix += gridDim.x) {
;     const int nx = tix + gridDim.x;
;     f32x4 n0 = c0, n1 = c1;
;     if (nx < ntiles) { const float* sp = tile_src(nx); n0 = *(const f32x4*)sp; n1 = *(const f32x4*)(sp + (size_t)32 * ld); }
.LBB0_59:
	s_waitcnt vmcnt(1)
	v_mov_b64_e32 v[14:15], v[2:3]
	s_waitcnt vmcnt(0)
	v_mov_b64_e32 v[10:11], v[6:7]
	s_andn2_b64 vcc, exec, s[8:9]
	v_mov_b64_e32 v[12:13], v[0:1]
	v_mov_b64_e32 v[8:9], v[4:5]
	s_cbranch_vccnz .LBB0_56
	s_ashr_i32 s8, s12, 31
	s_lshr_b32 s8, s8, 27
	s_add_i32 s8, s12, s8
	s_ashr_i32 s9, s8, 5
	v_lshl_add_u32 v8, s9, 6, v20
	s_add_i32 s13, s10, s11
	s_lshl_b32 s8, s9, 11
	v_ashrrev_i32_e32 v9, 31, v8
	v_readlane_b32 s16, v252, 22
	s_sub_i32 s8, s13, s8
	v_lshlrev_b64 v[8:9], 13, v[8:9]
	v_readlane_b32 s30, v252, 36
	v_readlane_b32 s31, v252, 37
	s_ashr_i32 s9, s8, 31
	v_readlane_b32 s17, v252, 23
	v_lshl_add_u64 v[8:9], s[30:31], 0, v[8:9]
	v_lshl_add_u64 v[8:9], s[8:9], 2, v[8:9]
	v_lshl_add_u64 v[8:9], v[8:9], 0, v[16:17]
	v_add_co_u32_e32 v12, vcc, 0x40000, v8
	v_readlane_b32 s18, v252, 24
	s_nop 0
	v_addc_co_u32_e32 v13, vcc, 0, v9, vcc
	global_load_dwordx4 v[8:11], v[8:9], off nt
	s_nop 0
	global_load_dwordx4 v[12:15], v[12:13], off nt
	v_readlane_b32 s19, v252, 25
	v_readlane_b32 s20, v252, 26
	v_readlane_b32 s21, v252, 27
	v_readlane_b32 s22, v252, 28
	v_readlane_b32 s23, v252, 29
	v_readlane_b32 s24, v252, 30
	v_readlane_b32 s25, v252, 31
	v_readlane_b32 s26, v252, 32
	v_readlane_b32 s27, v252, 33
	v_readlane_b32 s28, v252, 34
	v_readlane_b32 s29, v252, 35
	s_branch .LBB0_56
.LBB0_61:
	v_cndmask_b32_e64 v0, 0, 1, s[6:7]
	v_cmp_ne_u32_e64 s[4:5], 1, v0
	s_andn2_b64 vcc, exec, s[6:7]
	v_mov_b32 v8, v231
	s_nop 0
	v_writelane_b32 v252, s4, 48
	s_nop 1
	v_writelane_b32 v252, s5, 49
	s_cbranch_vccnz .LBB0_68
	s_add_u32 s12, s44, 0x2c00000
	s_addc_u32 s13, s45, 0
	s_add_u32 s14, s46, 0x2c00000
	s_addc_u32 s15, s47, 0
	s_add_u32 s4, s88, 0x9200000
	v_readlane_b32 s16, v252, 6
	s_addc_u32 s5, s89, 0
	v_readlane_b32 s22, v252, 12
	v_readlane_b32 s23, v252, 13
	s_add_u32 s6, s22, 0x2000
	s_addc_u32 s7, s23, 0
	s_lshr_b32 s8, s3, 31
	s_ashr_i32 s3, s3, 5
	s_add_i32 s3, s3, s8
	s_mul_i32 s8, s3, 0xb0
	s_sub_i32 s8, s65, s8
	s_lshl_b32 s9, s8, 6
	s_and_b32 s9, s9, 64
	s_bitcmp0_b32 s8, 1
	v_ashrrev_i32_e32 v20, 4, v8
	s_cselect_b32 s10, s13, s15
	s_cselect_b32 s11, s12, s14
	s_lshl_b32 s8, s8, 5
	v_mov_b32_e32 v0, s11
	v_mov_b32_e32 v1, s10
	s_and_b32 s8, s8, 0xffffff80
	v_lshl_add_u32 v2, s3, 6, v20
	s_movk_i32 s3, 0x5800
	s_or_b32 s8, s8, s9
	v_mad_i64_i32 v[0:1], s[10:11], v2, s3, v[0:1]
	v_lshlrev_b32_e32 v2, 2, v8
	s_ashr_i32 s9, s8, 31
	v_and_b32_e32 v10, 60, v2
	v_lshl_add_u64 v[0:1], s[8:9], 2, v[0:1]
	v_mov_b32_e32 v17, 0
	v_lshlrev_b32_e32 v16, 2, v10
	v_lshl_add_u64 v[0:1], v[0:1], 0, v[16:17]
	s_mov_b32 s8, 0xb0000
	v_add_co_u32_e32 v2, vcc, s8, v0
	s_movk_i32 s8, 0x104
	s_nop 0
	v_addc_co_u32_e32 v3, vcc, 0, v1, vcc
	global_load_dwordx4 v[4:7], v[2:3], off nt
	s_nop 0
	global_load_dwordx4 v[0:3], v[0:1], off nt
	v_ashrrev_i32_e32 v22, 3, v8
	v_lshlrev_b32_e32 v8, 3, v8
	v_mul_lo_u32 v9, v20, s8
	v_and_b32_e32 v8, 56, v8
	v_add3_u32 v21, 0, v9, v16
	v_lshl_add_u32 v9, v22, 2, 0
	v_mul_u32_u24_e32 v11, 0x104, v8
	v_readlane_b32 s17, v252, 7
	v_readlane_b32 s18, v252, 8
	v_readlane_b32 s19, v252, 9
	s_add_i32 s8, s90, s65
	v_add_u32_e32 v25, v9, v11
	s_lshl_b32 s17, s65, 6
	s_lshl_b32 s16, s90, 6
	s_lshl_b32 s18, s8, 5
	s_lshl_b32 s19, s90, 5
	v_lshlrev_b32_e32 v16, 2, v10
	v_add_u32_e32 v23, 0x2080, v21
	v_add_u32_e32 v24, 0x2088, v21
	v_lshlrev_b32_e32 v18, 1, v8
	v_mov_b32_e32 v19, v17
	v_add_u32_e32 v26, 0x400, v25
	s_mov_b32 s22, s65
	v_readlane_b32 s20, v252, 10
	v_readlane_b32 s21, v252, 11
	v_readlane_b32 s24, v252, 14
	v_readlane_b32 s25, v252, 15
	v_readlane_b32 s26, v252, 16
	v_readlane_b32 s27, v252, 17
	v_readlane_b32 s28, v252, 18
	v_readlane_b32 s29, v252, 19
	v_readlane_b32 s30, v252, 20
	v_readlane_b32 s31, v252, 21
	s_branch .LBB0_64

; __device__ __forceinline__ int opaque_tid() { int t; asm volatile("v_mov_b32 %0, %1" : "=v"(t) : "v"(threadIdx.x)); return t; }
; __device__ __forceinline__ void prep_weight(const float* src0, const float* src1, bf16_t* dst, int Nd, int K, int ld, int mode, float* tile, const float* wn = nullptr) {
;   const int tid = opaque_tid();
;   const int ntp = Nd >> 6, ntk = K >> 6, ntiles = ntp * ntk;
;   const int kl0 = tid >> 4, c4 = tid & 15;
;   auto tile_src = [&](int tix) -> const float* {
;     const int tp = tix % ntp, tk = tix / ntp;
;     const int p0 = tp * 64, k0 = tk * 64;
;     const float* src = src0; int col0 = p0;
;     if (mode == 1) { const int pn = p0 >> 8, rem = p0 & 255, bj = rem >> 7, j = rem & 127; src = bj ? src1 : src0; col0 = pn * 128 + j; }
;     else if (mode == 2) { const int t256 = p0 >> 8, rem = p0 & 255, bj = rem >> 7, w = rem & 127, head2 = w >> 6; col0 = t256 * 256 + head2 * 128 + bj * 64; }
;     return src + (size_t)(k0 + kl0) * ld + col0 + c4 * 4;
;   };
;   int tix = blockIdx.x;
;   f32x4 c0 = {0.f, 0.f, 0.f, 0.f}, c1 = c0;
;   if (tix < ntiles) { const float* sp = tile_src(tix); c0 = *(const f32x4*)sp; c1 = *(const f32x4*)(sp + (size_t)32 * ld); }
;   for (; tix < ntiles; tix += gridDim.x) {
;     const int nx = tix + gridDim.x;
;     f32x4 n0 = c0, n1 = c1;
;     if (nx < ntiles) { const float* sp = tile_src(nx); n0 = *(const f32x4*)sp; n1 = *(const f32x4*)(sp + (size_t)32 * ld); }
.LBB0_66:
	s_waitcnt vmcnt(1)
	v_mov_b64_e32 v[10:11], v[6:7]
	s_waitcnt vmcnt(0)
	v_mov_b64_e32 v[14:15], v[2:3]
	s_andn2_b64 vcc, exec, s[10:11]
	v_mov_b64_e32 v[8:9], v[4:5]
	v_mov_b64_e32 v[12:13], v[0:1]
	s_cbranch_vccnz .LBB0_63
	s_mul_hi_i32 s10, s20, 0x2e8ba2e9
	s_lshr_b32 s11, s10, 31
	s_ashr_i32 s10, s10, 5
	s_add_i32 s21, s16, s17
	s_add_i32 s11, s10, s11
	s_and_b32 s10, s21, 64
	s_bitcmp0_b32 s20, 1
	s_cselect_b32 s23, s13, s15
	v_mov_b32_e32 v9, s23
	s_mul_i32 s23, s11, 0xffffea00
	s_cselect_b32 s24, s12, s14
	s_add_i32 s23, s18, s23
	s_and_b32 s23, s23, 0xffffff80
	v_mov_b32_e32 v8, s24
	s_or_b32 s10, s23, s10
	v_lshl_add_u32 v10, s11, 6, v20
	v_mad_i64_i32 v[8:9], s[24:25], v10, s3, v[8:9]
	s_ashr_i32 s11, s10, 31
	v_lshl_add_u64 v[8:9], s[10:11], 2, v[8:9]
	v_lshl_add_u64 v[8:9], v[8:9], 0, v[16:17]
	v_add_co_u32_e32 v10, vcc, 0xb0000, v8
	s_nop 1
	v_addc_co_u32_e32 v11, vcc, 0, v9, vcc
	global_load_dwordx4 v[12:15], v[8:9], off nt
	s_nop 0
	global_load_dwordx4 v[8:11], v[10:11], off nt
	s_branch .LBB0_63
.LBB0_68:
	s_andn2_b64 vcc, exec, s[0:1]
	v_mov_b32 v8, v231
	s_cbranch_vccnz .LBB0_75
	s_add_u32 s0, s48, 0x2c00000
	s_addc_u32 s1, s49, 0
	s_add_u32 s4, s88, 0xbe00000
	s_addc_u32 s5, s89, 0
	s_ashr_i32 s3, s65, 31
	s_lshr_b32 s3, s3, 27
	s_add_i32 s3, s65, s3
	s_and_b32 s6, s3, 0x3ffffe0
	s_lshl_b32 s3, s3, 1
	v_ashrrev_i32_e32 v22, 4, v8
	s_andn2_b32 s3, s3, 63
	v_add_u32_e32 v0, s3, v22
	s_sub_i32 s6, s65, s6
	v_ashrrev_i32_e32 v1, 31, v0
	s_lshl_b32 s6, s6, 6
	v_lshlrev_b64 v[0:1], 13, v[0:1]
	v_lshlrev_b32_e32 v2, 2, v8
	v_lshl_add_u64 v[0:1], s[0:1], 0, v[0:1]
	s_ashr_i32 s7, s6, 31
	v_and_b32_e32 v10, 60, v2
	v_lshl_add_u64 v[0:1], s[6:7], 2, v[0:1]
	v_mov_b32_e32 v17, 0
	v_lshlrev_b32_e32 v16, 2, v10
	v_lshl_add_u64 v[4:5], v[0:1], 0, v[16:17]
	s_mov_b32 s3, 0x40000
	v_add_co_u32_e32 v0, vcc, s3, v4
	s_movk_i32 s3, 0x104
	s_nop 0
	v_addc_co_u32_e32 v1, vcc, 0, v5, vcc
	global_load_dwordx4 v[0:3], v[0:1], off nt
	s_nop 0
	global_load_dwordx4 v[4:7], v[4:5], off nt
	v_ashrrev_i32_e32 v24, 3, v8
	v_lshlrev_b32_e32 v8, 3, v8
	v_mul_lo_u32 v9, v22, s3
	v_and_b32_e32 v8, 56, v8
	v_add3_u32 v23, 0, v9, v16
	v_lshl_add_u32 v9, v24, 2, 0
	v_mul_u32_u24_e32 v11, 0x104, v8
	v_add_u32_e32 v27, v9, v11
	s_lshl_b32 s9, s65, 6
	s_lshl_b32 s3, s90, 6
	v_lshlrev_b32_e32 v16, 2, v10
	v_add_u32_e32 v25, 0x2080, v23
	v_add_u32_e32 v26, 0x2088, v23
	s_movk_i32 s8, 0x2c00
	v_mov_b64_e32 v[18:19], s[4:5]
	v_lshlrev_b32_e32 v20, 1, v8
	v_mov_b32_e32 v21, v17
	v_add_u32_e32 v28, 0x400, v27
	s_mov_b32 s12, s65
	s_branch .LBB0_71

; __device__ __forceinline__ void prep_weight(const float* src0, const float* src1, bf16_t* dst, int Nd, int K, int ld, int mode, float* tile, const float* wn = nullptr) {
;     ...
;   if (tix < ntiles) { const float* sp = tile_src(tix); c0 = *(const f32x4*)sp; c1 = *(const f32x4*)(sp + (size_t)32 * ld); }
;   for (; tix < ntiles; tix += gridDim.x) {
;     const int nx = tix + gridDim.x;
;     f32x4 n0 = c0, n1 = c1;
;     if (nx < ntiles) { const float* sp = tile_src(nx); n0 = *(const f32x4*)sp; n1 = *(const f32x4*)(sp + (size_t)32 * ld); }
.LBB0_73:
	s_waitcnt vmcnt(1)
	v_mov_b64_e32 v[14:15], v[2:3]
	s_waitcnt vmcnt(0)
	v_mov_b64_e32 v[10:11], v[6:7]
	s_andn2_b64 vcc, exec, s[6:7]
	v_mov_b64_e32 v[12:13], v[0:1]
	v_mov_b64_e32 v[8:9], v[4:5]
	s_cbranch_vccnz .LBB0_70
	s_ashr_i32 s6, s10, 31
	s_lshr_b32 s6, s6, 27
	s_add_i32 s6, s10, s6
	s_ashr_i32 s7, s6, 5
	v_lshl_add_u32 v8, s7, 6, v22
	s_add_i32 s11, s3, s9
	s_lshl_b32 s6, s7, 11
	v_ashrrev_i32_e32 v9, 31, v8
	s_sub_i32 s6, s11, s6
	v_lshlrev_b64 v[8:9], 13, v[8:9]
	v_lshl_add_u64 v[8:9], s[0:1], 0, v[8:9]
	s_ashr_i32 s7, s6, 31
	v_lshl_add_u64 v[8:9], s[6:7], 2, v[8:9]
	v_lshl_add_u64 v[8:9], v[8:9], 0, v[16:17]
	v_add_co_u32_e32 v12, vcc, 0x40000, v8
	s_nop 1
	v_addc_co_u32_e32 v13, vcc, 0, v9, vcc
	global_load_dwordx4 v[8:11], v[8:9], off nt
	s_nop 0
	global_load_dwordx4 v[12:15], v[12:13], off nt
	s_branch .LBB0_70

; __device__ __forceinline__ int opaque_tid() { int t; asm volatile("v_mov_b32 %0, %1" : "=v"(t) : "v"(threadIdx.x)); return t; }
; __device__ __forceinline__ float wave_sum(float v) {
; #pragma unroll
;   for (int o = 32; o >= 1; o >>= 1) v += __shfl_xor(v, o, 64);
;   return v;
; }
; template <bool OUTBF>
; __device__ __forceinline__ void rmsnorm_rows(const float* x0, const float* x1, const float* w, bf16_t* A, float* outf) {
;   const int tid_ = opaque_tid(); const int lane = tid_ & 63, wid = tid_ >> 6;
;   const int nw = gridDim.x * 8;
;   f32x4 wv[8];
; #pragma unroll
;   for (int j = 0; j < 8; ++j) wv[j] = *(const f32x4*)(w + (lane + 64 * j) * 4);
;   for (int row = blockIdx.x * 8 + wid; row < T_TOK; row += nw) {
.LBB0_85:
	s_or_b64 exec, exec, s[4:5]
	s_add_u32 s76, s88, 0xd400000
	s_addc_u32 s77, s89, 0
	v_mov_b32 v0, v231
	s_lshl_b32 s0, s65, 3
	v_ashrrev_i32_e32 v1, 6, v0
	v_writelane_b32 v252, s0, 50
	v_add_u32_e32 v40, s0, v1
	s_mov_b32 s0, 0x8000
	s_lshl_b32 s48, s90, 3
	v_cmp_gt_i32_e32 vcc, s0, v40
	v_mbcnt_lo_u32_b32 v60, -1, 0
	s_and_saveexec_b64 s[0:1], vcc
	s_cbranch_execz .LBB0_90
	v_lshlrev_b32_e32 v0, 2, v0
	v_and_b32_e32 v32, 0xfc, v0
	v_readlane_b32 s4, v252, 6
	v_lshlrev_b32_e32 v12, 2, v32
	v_readlane_b32 s8, v252, 10
	v_readlane_b32 s9, v252, 11
	s_nop 4
	global_load_dwordx4 v[0:3], v12, s[8:9] nt
	global_load_dwordx4 v[4:7], v12, s[8:9] offset:1024 nt
	global_load_dwordx4 v[8:11], v12, s[8:9] offset:2048 nt
	s_nop 0
	global_load_dwordx4 v[12:15], v12, s[8:9] offset:3072 nt
	v_or_b32_e32 v34, 0x400, v32
	v_or_b32_e32 v36, 0x500, v32
	v_or_b32_e32 v38, 0x600, v32
	v_or_b32_e32 v54, 0x700, v32
	v_lshlrev_b32_e32 v16, 2, v34
	v_lshlrev_b32_e32 v20, 2, v36
	v_lshlrev_b32_e32 v24, 2, v38
	v_lshlrev_b32_e32 v28, 2, v54
	global_load_dwordx4 v[16:19], v16, s[8:9] nt
	s_nop 0
	global_load_dwordx4 v[20:23], v20, s[8:9] nt
	s_nop 0
	global_load_dwordx4 v[24:27], v24, s[8:9] nt
	s_nop 0
	global_load_dwordx4 v[28:31], v28, s[8:9] nt
	v_mbcnt_hi_u32_b32 v33, -1, v60
	v_and_b32_e32 v35, 64, v33
	v_add_u32_e32 v35, 64, v35
	v_xor_b32_e32 v37, 32, v33
	v_cmp_lt_i32_e32 vcc, v37, v35
	v_ashrrev_i32_e32 v41, 31, v40
	v_readlane_b32 s5, v252, 7
	v_cndmask_b32_e32 v37, v33, v37, vcc
	v_lshlrev_b32_e32 v61, 2, v37
	v_xor_b32_e32 v37, 16, v33
	v_cmp_lt_i32_e32 vcc, v37, v35
	v_readlane_b32 s6, v252, 8
	v_readlane_b32 s7, v252, 9
	v_cndmask_b32_e32 v37, v33, v37, vcc
	v_lshlrev_b32_e32 v62, 2, v37
	v_xor_b32_e32 v37, 8, v33
	v_cmp_lt_i32_e32 vcc, v37, v35
	v_readlane_b32 s10, v252, 12
	v_readlane_b32 s11, v252, 13
	v_cndmask_b32_e32 v37, v33, v37, vcc
	v_lshlrev_b32_e32 v63, 2, v37
	v_xor_b32_e32 v37, 4, v33
	v_cmp_lt_i32_e32 vcc, v37, v35
	v_mov_b32_e32 v43, 0
	v_lshlrev_b32_e32 v42, 1, v32
	v_cndmask_b32_e32 v37, v33, v37, vcc
	v_lshlrev_b32_e32 v64, 2, v37
	v_xor_b32_e32 v37, 2, v33
	v_cmp_lt_i32_e32 vcc, v37, v35
	s_ashr_i32 s49, s48, 31
	v_lshlrev_b64 v[46:47], 13, v[40:41]
	v_cndmask_b32_e32 v37, v33, v37, vcc
	v_lshlrev_b32_e32 v65, 2, v37
	v_xor_b32_e32 v37, 1, v33
	v_cmp_lt_i32_e32 vcc, v37, v35
	v_lshl_add_u64 v[44:45], s[76:77], 0, v[42:43]
	v_lshl_add_u64 v[46:47], s[4:5], 0, v[46:47]
	v_cndmask_b32_e32 v33, v33, v37, vcc
	v_lshlrev_b32_e32 v66, 2, v33
	s_lshl_b64 s[4:5], s[48:49], 13
	s_mov_b64 s[6:7], 0
	s_movk_i32 s3, 0x3fff
	v_lshlrev_b32_e32 v42, 2, v32
	v_lshlrev_b32_e32 v48, 2, v34
	v_lshlrev_b32_e32 v50, 2, v36
	v_lshlrev_b32_e32 v52, 2, v38
	v_lshlrev_b32_e32 v54, 2, v54
	v_mov_b32_e32 v67, 0x3727c5ac
	s_mov_b32 s10, 0x800000
	s_movk_i32 s11, 0x7fff
	v_readlane_b32 s12, v252, 14
	v_readlane_b32 s13, v252, 15
	v_readlane_b32 s14, v252, 16
	v_readlane_b32 s15, v252, 17
	v_readlane_b32 s16, v252, 18
	v_readlane_b32 s17, v252, 19
	v_readlane_b32 s18, v252, 20
	v_readlane_b32 s19, v252, 21
	s_branch .LBB0_88
; __device__ __forceinline__ unsigned cvt_pk_bf16(float lo, float hi) { const f32v2_t v = {lo, hi}; const bf16v2_t b = __builtin_convertvector(v, bf16v2_t); return __builtin_bit_cast(unsigned, b); }
; __device__ __forceinline__ float wave_sum(float v) {
; #pragma unroll
;   for (int o = 32; o >= 1; o >>= 1) v += __shfl_xor(v, o, 64);
;   return v;
; }
; template <bool OUTBF>
; __device__ __forceinline__ void rmsnorm_rows(const float* x0, const float* x1, const float* w, bf16_t* A, float* outf) {
;     ...
;   for (int row = blockIdx.x * 8 + wid; row < T_TOK; row += nw) {
;     const float* xp = row < TP ? x0 + (size_t)row * DM : x1 + (size_t)(row - TP) * DM;
;     f32x4 v[8]; float ss = 0.f;
; #pragma unroll
;     for (int j = 0; j < 8; ++j) { v[j] = *(const f32x4*)(xp + (lane + 64 * j) * 4); ss += v[j][0] * v[j][0] + v[j][1] * v[j][1] + v[j][2] * v[j][2] + v[j][3] * v[j][3]; }
;     ss = wave_sum(ss);
;     const float rstd = rsqrtf(ss * (1.f / DM) + NORM_EPS);
; #pragma unroll
;     for (int j = 0; j < 8; ++j) { const f32x4 y = v[j] * rstd * wv[j];
;       if (OUTBF) { u32x2 o; o.x = cvt_pk_bf16(y[0], y[1]); o.y = cvt_pk_bf16(y[2], y[3]); *(u32x2*)(A + (size_t)row * DM + (lane + 64 * j) * 4) = o; }
;       else *(f32x4*)(outf + (size_t)row * DM + (lane + 64 * j) * 4) = y; }
;   }
.LBB0_87:
	s_or_b64 exec, exec, s[8:9]
	v_mov_b32_e32 v49, v43
	v_mov_b32_e32 v51, v43
	v_lshl_add_u64 v[32:33], v[58:59], 0, v[48:49]
	v_lshl_add_u64 v[34:35], v[58:59], 0, v[50:51]
	v_lshl_add_u64 v[80:81], v[58:59], 0, v[42:43]
	global_load_dwordx4 v[36:39], v[32:33], off nt
	s_nop 0
	global_load_dwordx4 v[32:35], v[34:35], off nt
	s_nop 0
	global_load_dwordx4 v[68:71], v[80:81], off nt
	global_load_dwordx4 v[72:75], v[80:81], off offset:1024 nt
	global_load_dwordx4 v[76:79], v[80:81], off offset:2048 nt
	s_nop 0
	global_load_dwordx4 v[80:83], v[80:81], off offset:3072 nt
	v_mov_b32_e32 v53, v43
	v_mov_b32_e32 v55, v43
	v_lshl_add_u64 v[84:85], v[58:59], 0, v[52:53]
	v_lshl_add_u64 v[58:59], v[58:59], 0, v[54:55]
	global_load_dwordx4 v[84:87], v[84:85], off nt
	s_nop 0
	global_load_dwordx4 v[88:91], v[58:59], off nt
	v_lshl_add_u64 v[40:41], v[40:41], 0, s[48:49]
	v_lshlrev_b64 v[56:57], 12, v[56:57]
	v_lshl_add_u64 v[56:57], v[44:45], 0, v[56:57]
	v_lshl_add_u64 v[46:47], v[46:47], 0, s[4:5]
	s_waitcnt vmcnt(5)
	v_mul_f32_e32 v49, v69, v69
	s_waitcnt vmcnt(4)
	v_mul_f32_e32 v51, v73, v73
	s_waitcnt vmcnt(3)
	v_mul_f32_e32 v53, v77, v77
	v_fmac_f32_e32 v49, v68, v68
	v_fmac_f32_e32 v51, v72, v72
	s_waitcnt vmcnt(2)
	v_mul_f32_e32 v55, v81, v81
	v_mov_b32_e32 v92, v37
	v_mov_b32_e32 v93, v33
	v_fmac_f32_e32 v53, v76, v76
	v_fmac_f32_e32 v49, v70, v70
	v_fmac_f32_e32 v51, v74, v74
	v_mov_b32_e32 v58, v36
	v_mov_b32_e32 v59, v32
	v_fmac_f32_e32 v55, v80, v80
	v_pk_mul_f32 v[92:93], v[92:93], v[92:93]
	v_fmac_f32_e32 v53, v78, v78
	v_fmac_f32_e32 v49, v71, v71
	v_fmac_f32_e32 v51, v75, v75
	s_waitcnt vmcnt(1)
	v_mov_b32_e32 v96, v85
	s_waitcnt vmcnt(0)
	v_mov_b32_e32 v97, v89
	v_mov_b32_e32 v98, v38
	v_mov_b32_e32 v99, v34
	v_fmac_f32_e32 v55, v82, v82
	v_pk_fma_f32 v[58:59], v[58:59], v[58:59], v[92:93]
	v_fmac_f32_e32 v53, v79, v79
	v_add_f32_e32 v49, v49, v51
	v_mov_b32_e32 v94, v84
	v_mov_b32_e32 v95, v88
	v_mov_b32_e32 v102, v39
	v_mov_b32_e32 v103, v35
	v_pk_mul_f32 v[96:97], v[96:97], v[96:97]
	v_fmac_f32_e32 v55, v83, v83
	v_pk_fma_f32 v[58:59], v[98:99], v[98:99], v[58:59]
	v_add_f32_e32 v49, v49, v53
	v_mov_b32_e32 v100, v86
	v_mov_b32_e32 v101, v90
	v_pk_fma_f32 v[92:93], v[94:95], v[94:95], v[96:97]
	v_pk_fma_f32 v[58:59], v[102:103], v[102:103], v[58:59]
	v_add_f32_e32 v49, v49, v55
	v_mov_b32_e32 v104, v87
	v_mov_b32_e32 v105, v91
	v_pk_fma_f32 v[92:93], v[100:101], v[100:101], v[92:93]
	v_add_f32_e32 v49, v49, v58
	v_pk_fma_f32 v[92:93], v[104:105], v[104:105], v[92:93]
	v_add_f32_e32 v49, v49, v59
	v_add_f32_e32 v49, v49, v92
	v_add_f32_e32 v49, v49, v93
	ds_bpermute_b32 v51, v61, v49
	s_waitcnt lgkmcnt(0)
	v_add_f32_e32 v49, v49, v51
	ds_bpermute_b32 v51, v62, v49
	s_waitcnt lgkmcnt(0)
	v_add_f32_e32 v49, v49, v51
	ds_bpermute_b32 v51, v63, v49
	s_waitcnt lgkmcnt(0)
	v_add_f32_e32 v49, v49, v51
	ds_bpermute_b32 v51, v64, v49
	s_waitcnt lgkmcnt(0)
	v_add_f32_e32 v49, v49, v51
	ds_bpermute_b32 v51, v65, v49
	s_waitcnt lgkmcnt(0)
	v_add_f32_e32 v49, v49, v51
	ds_bpermute_b32 v51, v66, v49
	s_waitcnt lgkmcnt(0)
	v_add_f32_e32 v49, v49, v51
	v_fmamk_f32 v49, v49, 0x3a000000, v67
	v_mul_f32_e32 v51, 0x4b800000, v49
	v_cmp_gt_f32_e32 vcc, s10, v49
	s_nop 1
	v_cndmask_b32_e32 v49, v49, v51, vcc
	v_rsq_f32_e32 v49, v49
	s_nop 0
	v_mul_f32_e32 v51, 0x45800000, v49
	v_cndmask_b32_e32 v58, v49, v51, vcc
	v_pk_mul_f32 v[68:69], v[68:69], v[58:59] op_sel_hi:[1,0]
	v_pk_mul_f32 v[70:71], v[70:71], v[58:59] op_sel_hi:[1,0]
	v_pk_mul_f32 v[72:73], v[72:73], v[58:59] op_sel_hi:[1,0]
	v_pk_mul_f32 v[74:75], v[74:75], v[58:59] op_sel_hi:[1,0]
	v_pk_mul_f32 v[76:77], v[76:77], v[58:59] op_sel_hi:[1,0]
	v_pk_mul_f32 v[78:79], v[78:79], v[58:59] op_sel_hi:[1,0]
	v_pk_mul_f32 v[80:81], v[80:81], v[58:59] op_sel_hi:[1,0]
	v_pk_mul_f32 v[82:83], v[82:83], v[58:59] op_sel_hi:[1,0]
	v_pk_mul_f32 v[36:37], v[36:37], v[58:59] op_sel_hi:[1,0]
	v_pk_mul_f32 v[38:39], v[38:39], v[58:59] op_sel_hi:[1,0]
	v_pk_mul_f32 v[32:33], v[32:33], v[58:59] op_sel_hi:[1,0]
	v_pk_mul_f32 v[34:35], v[34:35], v[58:59] op_sel_hi:[1,0]
	v_pk_mul_f32 v[84:85], v[84:85], v[58:59] op_sel_hi:[1,0]
	v_pk_mul_f32 v[86:87], v[86:87], v[58:59] op_sel_hi:[1,0]
	v_pk_mul_f32 v[88:89], v[88:89], v[58:59] op_sel_hi:[1,0]
	v_pk_mul_f32 v[58:59], v[90:91], v[58:59] op_sel_hi:[1,0]
	v_pk_mul_f32 v[70:71], v[2:3], v[70:71]
	v_pk_mul_f32 v[68:69], v[0:1], v[68:69]
	v_cmp_lt_i32_e32 vcc, s11, v40
	v_pk_mul_f32 v[74:75], v[6:7], v[74:75]
	v_pk_mul_f32 v[72:73], v[4:5], v[72:73]
	v_pk_mul_f32 v[78:79], v[10:11], v[78:79]
	v_pk_mul_f32 v[76:77], v[8:9], v[76:77]
	v_pk_mul_f32 v[82:83], v[14:15], v[82:83]
	v_pk_mul_f32 v[80:81], v[12:13], v[80:81]
	v_pk_mul_f32 v[38:39], v[18:19], v[38:39]
	v_pk_mul_f32 v[36:37], v[16:17], v[36:37]
	v_pk_mul_f32 v[34:35], v[22:23], v[34:35]
	v_pk_mul_f32 v[32:33], v[20:21], v[32:33]
	v_pk_mul_f32 v[86:87], v[26:27], v[86:87]
	v_pk_mul_f32 v[84:85], v[24:25], v[84:85]
	v_pk_mul_f32 v[58:59], v[30:31], v[58:59]
	v_pk_mul_f32 v[88:89], v[28:29], v[88:89]
	v_cvt_pk_bf16_f32 v68, v68, v69
	v_cvt_pk_bf16_f32 v69, v70, v71
	s_or_b64 s[6:7], vcc, s[6:7]
	v_cvt_pk_bf16_f32 v70, v72, v73
	v_cvt_pk_bf16_f32 v71, v74, v75
	v_cvt_pk_bf16_f32 v72, v76, v77
	v_cvt_pk_bf16_f32 v73, v78, v79
	v_cvt_pk_bf16_f32 v74, v80, v81
	v_cvt_pk_bf16_f32 v75, v82, v83
	v_cvt_pk_bf16_f32 v36, v36, v37
	v_cvt_pk_bf16_f32 v37, v38, v39
	v_cvt_pk_bf16_f32 v32, v32, v33
	v_cvt_pk_bf16_f32 v33, v34, v35
	v_cvt_pk_bf16_f32 v34, v84, v85
	v_cvt_pk_bf16_f32 v35, v86, v87
	v_cvt_pk_bf16_f32 v38, v88, v89
	v_cvt_pk_bf16_f32 v39, v58, v59
	global_store_dwordx2 v[56:57], v[68:69], off
	global_store_dwordx2 v[56:57], v[70:71], off offset:512
	global_store_dwordx2 v[56:57], v[72:73], off offset:1024
	global_store_dwordx2 v[56:57], v[74:75], off offset:1536
	global_store_dwordx2 v[56:57], v[36:37], off offset:2048
	global_store_dwordx2 v[56:57], v[32:33], off offset:2560
	global_store_dwordx2 v[56:57], v[34:35], off offset:3072
	global_store_dwordx2 v[56:57], v[38:39], off offset:3584
	s_andn2_b64 exec, exec, s[6:7]
	s_cbranch_execz .LBB0_90

; __device__ __forceinline__ unsigned cvt_pk_bf16(float lo, float hi) { const f32v2_t v = {lo, hi}; const bf16v2_t b = __builtin_convertvector(v, bf16v2_t); return __builtin_bit_cast(unsigned, b); }
; __device__ __forceinline__ float bflo(unsigned w) { return __uint_as_float(w << 16); }
; __device__ __forceinline__ float bfhi(unsigned w) { return __uint_as_float(w & 0xffff0000u); }
; __device__ __forceinline__ int opaque_tid() { int t; asm volatile("v_mov_b32 %0, %1" : "=v"(t) : "v"(threadIdx.x)); return t; }
; template <bool OUTBF>
; __device__ __forceinline__ void rmsnorm_rows_b(const bf16_t* Xb, const float* w, bf16_t* A, float* outf) {
;   const int tid_ = opaque_tid(); const int lane = tid_ & 63, wid = tid_ >> 6;
;   const int nw = gridDim.x * 8;
;   f32x4 wa[4], wb[4];
; #pragma unroll
;   for (int j = 0; j < 4; ++j) { wa[j] = *(const f32x4*)(w + (lane + 64 * j) * 8); wb[j] = *(const f32x4*)(w + (lane + 64 * j) * 8 + 4); }
;   for (int row = blockIdx.x * 8 + wid; row < T_TOK; row += nw) {
;     const bf16_t* xp = Xb + (size_t)row * DM;
;     u32x4 x[4]; float ss = 0.f;
; #pragma unroll
;     for (int j = 0; j < 4; ++j) x[j] = *(const u32x4*)(xp + (lane + 64 * j) * 8);
;     float v[4][8];
; #pragma unroll
;     for (int j = 0; j < 4; ++j) {
; #pragma unroll
;       for (int k = 0; k < 4; ++k) { v[j][2 * k] = bflo(x[j][k]); v[j][2 * k + 1] = bfhi(x[j][k]); }
; #pragma unroll
;       for (int k = 0; k < 8; ++k) ss += v[j][k] * v[j][k]; }
;     ss = wave_sum(ss);
;     const float rstd = rsqrtf(ss * (1.f / DM) + NORM_EPS);
; #pragma unroll
;     for (int j = 0; j < 4; ++j) { float y[8];
; #pragma unroll
;       for (int k = 0; k < 8; ++k) y[k] = v[j][k] * rstd * (k < 4 ? wa[j][k & 3] : wb[j][k & 3]);
;       if (OUTBF) { u32x4 o; o.x = cvt_pk_bf16(y[0], y[1]); o.y = cvt_pk_bf16(y[2], y[3]); o.z = cvt_pk_bf16(y[4], y[5]); o.w = cvt_pk_bf16(y[6], y[7]);
;         *(u32x4*)(A + (size_t)row * DM + (lane + 64 * j) * 8) = o; }
;       else { float* op = outf + (size_t)row * DM + (lane + 64 * j) * 8; *(f32x4*)op = (f32x4){y[0], y[1], y[2], y[3]}; *(f32x4*)(op + 4) = (f32x4){y[4], y[5], y[6], y[7]}; } }
;   }
.LBB0_1153:
	global_load_dwordx4 v[48:51], v[38:39], off nt
	global_load_dwordx4 v[52:55], v[38:39], off offset:1024 nt
	global_load_dwordx4 v[56:59], v[38:39], off offset:2048 nt
	global_load_dwordx4 v[32:35], v[38:39], off offset:3072 nt
	v_add_u32_e32 v36, s48, v36
	v_cmp_lt_i32_e32 vcc, s5, v36
	s_or_b64 s[2:3], vcc, s[2:3]
	v_lshl_add_u64 v[38:39], v[38:39], 0, s[16:17]
	s_waitcnt vmcnt(3)
	v_lshlrev_b32_e32 v62, 16, v48
	v_and_b32_e32 v63, 0xffff0000, v48
	v_lshlrev_b32_e32 v48, 16, v49
	v_and_b32_e32 v49, 0xffff0000, v49
	v_pk_mul_f32 v[80:81], v[62:63], v[62:63]
	v_pk_mul_f32 v[82:83], v[48:49], v[48:49]
	v_add_f32_e32 v80, v80, v81
	v_lshlrev_b32_e32 v60, 16, v50
	v_and_b32_e32 v61, 0xffff0000, v50
	v_add_f32_e32 v80, v82, v80
	v_pk_mul_f32 v[76:77], v[60:61], v[60:61]
	v_add_f32_e32 v80, v83, v80
	v_lshlrev_b32_e32 v50, 16, v51
	v_and_b32_e32 v51, 0xffff0000, v51
	v_add_f32_e32 v76, v76, v80
	v_pk_mul_f32 v[78:79], v[50:51], v[50:51]
	v_add_f32_e32 v76, v77, v76
	s_waitcnt vmcnt(2)
	v_lshlrev_b32_e32 v66, 16, v52
	v_and_b32_e32 v67, 0xffff0000, v52
	v_add_f32_e32 v76, v78, v76
	v_pk_mul_f32 v[88:89], v[66:67], v[66:67]
	v_add_f32_e32 v76, v79, v76
	v_lshlrev_b32_e32 v52, 16, v53
	v_and_b32_e32 v53, 0xffff0000, v53
	v_add_f32_e32 v76, v88, v76
	v_pk_mul_f32 v[90:91], v[52:53], v[52:53]
	v_add_f32_e32 v76, v89, v76
	v_lshlrev_b32_e32 v64, 16, v54
	v_and_b32_e32 v65, 0xffff0000, v54
	v_add_f32_e32 v76, v90, v76
	v_pk_mul_f32 v[84:85], v[64:65], v[64:65]
	v_add_f32_e32 v76, v91, v76
	v_lshlrev_b32_e32 v54, 16, v55
	v_and_b32_e32 v55, 0xffff0000, v55
	v_add_f32_e32 v76, v84, v76
	v_pk_mul_f32 v[86:87], v[54:55], v[54:55]
	v_add_f32_e32 v76, v85, v76
	s_waitcnt vmcnt(1)
	v_lshlrev_b32_e32 v70, 16, v56
	v_and_b32_e32 v71, 0xffff0000, v56
	v_add_f32_e32 v76, v86, v76
	v_pk_mul_f32 v[96:97], v[70:71], v[70:71]
	v_add_f32_e32 v76, v87, v76
	v_lshlrev_b32_e32 v56, 16, v57
	v_and_b32_e32 v57, 0xffff0000, v57
	v_add_f32_e32 v76, v96, v76
	v_pk_mul_f32 v[98:99], v[56:57], v[56:57]
	v_add_f32_e32 v76, v97, v76
	v_lshlrev_b32_e32 v68, 16, v58
	v_and_b32_e32 v69, 0xffff0000, v58
	v_add_f32_e32 v76, v98, v76
	v_pk_mul_f32 v[92:93], v[68:69], v[68:69]
	v_add_f32_e32 v76, v99, v76
	v_lshlrev_b32_e32 v58, 16, v59
	v_and_b32_e32 v59, 0xffff0000, v59
	v_add_f32_e32 v76, v92, v76
	v_pk_mul_f32 v[94:95], v[58:59], v[58:59]
	v_add_f32_e32 v76, v93, v76
	s_waitcnt vmcnt(0)
	v_lshlrev_b32_e32 v74, 16, v32
	v_and_b32_e32 v75, 0xffff0000, v32
	v_add_f32_e32 v76, v94, v76
	v_pk_mul_f32 v[104:105], v[74:75], v[74:75]
	v_add_f32_e32 v76, v95, v76
	v_lshlrev_b32_e32 v32, 16, v33
	v_and_b32_e32 v33, 0xffff0000, v33
	v_add_f32_e32 v76, v104, v76
	v_pk_mul_f32 v[106:107], v[32:33], v[32:33]
	v_add_f32_e32 v76, v105, v76
	v_lshlrev_b32_e32 v72, 16, v34
	v_and_b32_e32 v73, 0xffff0000, v34
	v_add_f32_e32 v76, v106, v76
	v_pk_mul_f32 v[100:101], v[72:73], v[72:73]
	v_add_f32_e32 v76, v107, v76
	v_lshlrev_b32_e32 v34, 16, v35
	v_and_b32_e32 v35, 0xffff0000, v35
	v_add_f32_e32 v76, v100, v76
	v_pk_mul_f32 v[102:103], v[34:35], v[34:35]
	v_add_f32_e32 v76, v101, v76
	v_add_f32_e32 v76, v102, v76
	v_add_f32_e32 v76, v103, v76
	ds_bpermute_b32 v77, v42, v76
	s_waitcnt lgkmcnt(0)
	v_add_f32_e32 v76, v76, v77
	ds_bpermute_b32 v77, v43, v76
	s_waitcnt lgkmcnt(0)
	v_add_f32_e32 v76, v76, v77
	ds_bpermute_b32 v77, v44, v76
	s_waitcnt lgkmcnt(0)
	v_add_f32_e32 v76, v76, v77
	ds_bpermute_b32 v77, v45, v76
	s_waitcnt lgkmcnt(0)
	v_add_f32_e32 v76, v76, v77
	ds_bpermute_b32 v77, v46, v76
	s_waitcnt lgkmcnt(0)
	v_add_f32_e32 v76, v76, v77
	ds_bpermute_b32 v77, v47, v76
	s_waitcnt lgkmcnt(0)
	v_add_f32_e32 v76, v76, v77
	v_fmamk_f32 v76, v76, 0x3a000000, v37
	v_mul_f32_e32 v77, 0x4b800000, v76
	v_cmp_gt_f32_e32 vcc, s4, v76
	s_nop 1
	v_cndmask_b32_e32 v76, v76, v77, vcc
	v_rsq_f32_e32 v76, v76
	s_nop 0
	v_mul_f32_e32 v77, 0x45800000, v76
	v_cndmask_b32_e32 v76, v76, v77, vcc
	v_pk_mul_f32 v[62:63], v[76:77], v[62:63] op_sel_hi:[0,1]
	v_pk_mul_f32 v[48:49], v[76:77], v[48:49] op_sel_hi:[0,1]
	v_pk_mul_f32 v[60:61], v[76:77], v[60:61] op_sel_hi:[0,1]
	v_pk_mul_f32 v[50:51], v[76:77], v[50:51] op_sel_hi:[0,1]
	v_pk_mul_f32 v[66:67], v[76:77], v[66:67] op_sel_hi:[0,1]
	v_pk_mul_f32 v[52:53], v[76:77], v[52:53] op_sel_hi:[0,1]
	v_pk_mul_f32 v[64:65], v[76:77], v[64:65] op_sel_hi:[0,1]
	v_pk_mul_f32 v[78:79], v[76:77], v[54:55] op_sel_hi:[0,1]
	v_pk_mul_f32 v[70:71], v[76:77], v[70:71] op_sel_hi:[0,1]
	v_pk_mul_f32 v[80:81], v[76:77], v[56:57] op_sel_hi:[0,1]
	v_pk_mul_f32 v[68:69], v[76:77], v[68:69] op_sel_hi:[0,1]
	v_pk_mul_f32 v[82:83], v[76:77], v[58:59] op_sel_hi:[0,1]
	v_pk_mul_f32 v[74:75], v[76:77], v[74:75] op_sel_hi:[0,1]
	v_pk_mul_f32 v[84:85], v[76:77], v[32:33] op_sel_hi:[0,1]
	v_pk_mul_f32 v[72:73], v[76:77], v[72:73] op_sel_hi:[0,1]
	v_pk_mul_f32 v[76:77], v[76:77], v[34:35] op_sel_hi:[0,1]
	v_pk_mul_f32 v[34:35], v[30:31], v[48:49]
	v_pk_mul_f32 v[32:33], v[28:29], v[62:63]
	v_pk_mul_f32 v[50:51], v[26:27], v[50:51]
	v_pk_mul_f32 v[48:49], v[24:25], v[60:61]
	v_pk_mul_f32 v[54:55], v[22:23], v[52:53]
	v_pk_mul_f32 v[52:53], v[20:21], v[66:67]
	v_pk_mul_f32 v[58:59], v[18:19], v[78:79]
	v_pk_mul_f32 v[56:57], v[16:17], v[64:65]
	v_pk_mul_f32 v[62:63], v[14:15], v[80:81]
	v_pk_mul_f32 v[60:61], v[12:13], v[70:71]
	v_pk_mul_f32 v[66:67], v[10:11], v[82:83]
	v_pk_mul_f32 v[64:65], v[8:9], v[68:69]
	v_pk_mul_f32 v[70:71], v[6:7], v[84:85]
	v_pk_mul_f32 v[68:69], v[4:5], v[74:75]
	v_pk_mul_f32 v[74:75], v[2:3], v[76:77]
	v_pk_mul_f32 v[72:73], v[0:1], v[72:73]
	global_store_dwordx4 v[40:41], v[32:35], off offset:-4096 nt
	global_store_dwordx4 v[40:41], v[48:51], off offset:-4080 nt
	global_store_dwordx4 v[40:41], v[52:55], off offset:-2048 nt
	global_store_dwordx4 v[40:41], v[56:59], off offset:-2032 nt
	global_store_dwordx4 v[40:41], v[60:63], off nt
	global_store_dwordx4 v[40:41], v[64:67], off offset:16 nt
	global_store_dwordx4 v[40:41], v[68:71], off offset:2048 nt
	global_store_dwordx4 v[40:41], v[72:75], off offset:2064 nt
	v_lshl_add_u64 v[40:41], v[40:41], 0, s[0:1]
	s_andn2_b64 exec, exec, s[2:3]
	s_cbranch_execnz .LBB0_1153
